# indexer radix-select loop: 2-slot counting with 3 rotating carry chains + DPP/swizzle reduction (on top of attention fixes + younger-half priority)
# speedup vs baseline: 1.0248x; 1.0060x over previous
.LBB0_652:
	v_lshlrev_b32_e64 v5, v2, 1
	v_or_b32_e32 v5, v66, v5
	v_add_u32_e32 v2, -1, v2
	v_mov_b32_e32 v6, 0
	v_mov_b32_e32 v7, 0
	v_mov_b32_e32 v8, 0
	v_cmp_ge_u32_e32 vcc, v175, v5
	v_cmp_ge_u32_e64 s[82:83], v3, v5
	v_cmp_ge_u32_e64 s[100:101], v176, v5
	v_addc_co_u32_e32 v6, vcc, 0, v6, vcc
	v_addc_co_u32_e64 v7, s[82:83], 0, v7, s[82:83]
	v_addc_co_u32_e64 v8, s[100:101], 0, v8, s[100:101]
	v_cmp_ge_u32_e32 vcc, v179, v5
	v_cmp_ge_u32_e64 s[82:83], v180, v5
	v_cmp_ge_u32_e64 s[100:101], v181, v5
	v_addc_co_u32_e32 v6, vcc, 0, v6, vcc
	v_addc_co_u32_e64 v7, s[82:83], 0, v7, s[82:83]
	v_addc_co_u32_e64 v8, s[100:101], 0, v8, s[100:101]
	v_cmp_ge_u32_e32 vcc, v182, v5
	v_cmp_ge_u32_e64 s[82:83], v183, v5
	v_cmp_ge_u32_e64 s[100:101], v184, v5
	v_addc_co_u32_e32 v6, vcc, 0, v6, vcc
	v_addc_co_u32_e64 v7, s[82:83], 0, v7, s[82:83]
	v_addc_co_u32_e64 v8, s[100:101], 0, v8, s[100:101]
	v_cmp_ge_u32_e32 vcc, v185, v5
	v_cmp_ge_u32_e64 s[82:83], v186, v5
	v_cmp_ge_u32_e64 s[100:101], v187, v5
	v_addc_co_u32_e32 v6, vcc, 0, v6, vcc
	v_addc_co_u32_e64 v7, s[82:83], 0, v7, s[82:83]
	v_addc_co_u32_e64 v8, s[100:101], 0, v8, s[100:101]
	v_cmp_ge_u32_e32 vcc, v188, v5
	v_cmp_ge_u32_e64 s[82:83], v189, v5
	v_cmp_ge_u32_e64 s[100:101], v190, v5
	v_addc_co_u32_e32 v6, vcc, 0, v6, vcc
	v_addc_co_u32_e64 v7, s[82:83], 0, v7, s[82:83]
	v_addc_co_u32_e64 v8, s[100:101], 0, v8, s[100:101]
	v_cmp_ge_u32_e32 vcc, v191, v5
	v_cmp_ge_u32_e64 s[82:83], v192, v5
	v_cmp_ge_u32_e64 s[100:101], v193, v5
	v_addc_co_u32_e32 v6, vcc, 0, v6, vcc
	v_addc_co_u32_e64 v7, s[82:83], 0, v7, s[82:83]
	v_addc_co_u32_e64 v8, s[100:101], 0, v8, s[100:101]
	v_cmp_ge_u32_e32 vcc, v194, v5
	v_cmp_ge_u32_e64 s[82:83], v195, v5
	v_cmp_ge_u32_e64 s[100:101], v196, v5
	v_addc_co_u32_e32 v6, vcc, 0, v6, vcc
	v_addc_co_u32_e64 v7, s[82:83], 0, v7, s[82:83]
	v_addc_co_u32_e64 v8, s[100:101], 0, v8, s[100:101]
	v_cmp_ge_u32_e32 vcc, v197, v5
	v_cmp_ge_u32_e64 s[82:83], v216, v5
	v_cmp_ge_u32_e64 s[100:101], v217, v5
	v_addc_co_u32_e32 v6, vcc, 0, v6, vcc
	v_addc_co_u32_e64 v7, s[82:83], 0, v7, s[82:83]
	v_addc_co_u32_e64 v8, s[100:101], 0, v8, s[100:101]
	v_cmp_ge_u32_e32 vcc, v218, v5
	v_cmp_ge_u32_e64 s[82:83], v219, v5
	v_cmp_ge_u32_e64 s[100:101], v220, v5
	v_addc_co_u32_e32 v6, vcc, 0, v6, vcc
	v_addc_co_u32_e64 v7, s[82:83], 0, v7, s[82:83]
	v_addc_co_u32_e64 v8, s[100:101], 0, v8, s[100:101]
	v_cmp_ge_u32_e32 vcc, v221, v5
	v_cmp_ge_u32_e64 s[82:83], v222, v5
	v_cmp_ge_u32_e64 s[100:101], v223, v5
	v_addc_co_u32_e32 v6, vcc, 0, v6, vcc
	v_addc_co_u32_e64 v7, s[82:83], 0, v7, s[82:83]
	v_addc_co_u32_e64 v8, s[100:101], 0, v8, s[100:101]
	v_cmp_ge_u32_e32 vcc, v224, v5
	v_cmp_ge_u32_e64 s[82:83], v225, v5
	v_cmp_ge_u32_e64 s[100:101], v226, v5
	v_addc_co_u32_e32 v6, vcc, 0, v6, vcc
	v_addc_co_u32_e64 v7, s[82:83], 0, v7, s[82:83]
	v_addc_co_u32_e64 v8, s[100:101], 0, v8, s[100:101]
	v_cmp_ge_u32_e32 vcc, v227, v5
	v_cmp_ge_u32_e64 s[82:83], v228, v5
	v_cmp_ge_u32_e64 s[100:101], v229, v5
	v_addc_co_u32_e32 v6, vcc, 0, v6, vcc
	v_addc_co_u32_e64 v7, s[82:83], 0, v7, s[82:83]
	v_addc_co_u32_e64 v8, s[100:101], 0, v8, s[100:101]
	v_cmp_ge_u32_e32 vcc, v230, v5
	v_cmp_ge_u32_e64 s[82:83], v231, v5
	v_cmp_ge_u32_e64 s[100:101], v232, v5
	v_addc_co_u32_e32 v6, vcc, 0, v6, vcc
	v_addc_co_u32_e64 v7, s[82:83], 0, v7, s[82:83]
	v_addc_co_u32_e64 v8, s[100:101], 0, v8, s[100:101]
	v_cmp_ge_u32_e32 vcc, v233, v5
	v_cmp_ge_u32_e64 s[82:83], v234, v5
	v_cmp_ge_u32_e64 s[100:101], v235, v5
	v_addc_co_u32_e32 v6, vcc, 0, v6, vcc
	v_addc_co_u32_e64 v7, s[82:83], 0, v7, s[82:83]
	v_addc_co_u32_e64 v8, s[100:101], 0, v8, s[100:101]
	v_cmp_ge_u32_e32 vcc, v236, v5
	v_cmp_ge_u32_e64 s[82:83], v237, v5
	v_cmp_ge_u32_e64 s[100:101], v238, v5
	v_addc_co_u32_e32 v6, vcc, 0, v6, vcc
	v_addc_co_u32_e64 v7, s[82:83], 0, v7, s[82:83]
	v_addc_co_u32_e64 v8, s[100:101], 0, v8, s[100:101]
	v_cmp_ge_u32_e32 vcc, v239, v5
	v_cmp_ge_u32_e64 s[82:83], v240, v5
	v_cmp_ge_u32_e64 s[100:101], v241, v5
	v_addc_co_u32_e32 v6, vcc, 0, v6, vcc
	v_addc_co_u32_e64 v7, s[82:83], 0, v7, s[82:83]
	v_addc_co_u32_e64 v8, s[100:101], 0, v8, s[100:101]
	v_cmp_ge_u32_e32 vcc, v242, v5
	v_cmp_ge_u32_e64 s[82:83], v243, v5
	v_cmp_ge_u32_e64 s[100:101], v244, v5
	v_addc_co_u32_e32 v6, vcc, 0, v6, vcc
	v_addc_co_u32_e64 v7, s[82:83], 0, v7, s[82:83]
	v_addc_co_u32_e64 v8, s[100:101], 0, v8, s[100:101]
	v_cmp_ge_u32_e32 vcc, v245, v5
	v_cmp_ge_u32_e64 s[82:83], v246, v5
	v_cmp_ge_u32_e64 s[100:101], v247, v5
	v_addc_co_u32_e32 v6, vcc, 0, v6, vcc
	v_addc_co_u32_e64 v7, s[82:83], 0, v7, s[82:83]
	v_addc_co_u32_e64 v8, s[100:101], 0, v8, s[100:101]
	v_cmp_ge_u32_e32 vcc, v248, v5
	v_cmp_ge_u32_e64 s[82:83], v249, v5
	v_cmp_ge_u32_e64 s[100:101], v250, v5
	v_addc_co_u32_e32 v6, vcc, 0, v6, vcc
	v_addc_co_u32_e64 v7, s[82:83], 0, v7, s[82:83]
	v_addc_co_u32_e64 v8, s[100:101], 0, v8, s[100:101]
	v_cmp_ge_u32_e32 vcc, v199, v5
	v_cmp_ge_u32_e64 s[82:83], v200, v5
	v_cmp_ge_u32_e64 s[100:101], v207, v5
	v_addc_co_u32_e32 v6, vcc, 0, v6, vcc
	v_addc_co_u32_e64 v7, s[82:83], 0, v7, s[82:83]
	v_addc_co_u32_e64 v8, s[100:101], 0, v8, s[100:101]
	v_cmp_ge_u32_e32 vcc, v208, v5
	v_cmp_ge_u32_e64 s[82:83], v210, v5
	v_cmp_ge_u32_e64 s[100:101], v70, v5
	v_addc_co_u32_e32 v6, vcc, 0, v6, vcc
	v_addc_co_u32_e64 v7, s[82:83], 0, v7, s[82:83]
	v_addc_co_u32_e64 v8, s[100:101], 0, v8, s[100:101]
	v_cmp_ge_u32_e32 vcc, v18, v5
	s_nop 1
	v_addc_co_u32_e32 v6, vcc, 0, v6, vcc
	v_add3_u32 v6, v6, v7, v8
	s_nop 1
	v_add_u32_dpp v6, v6, v6 quad_perm:[1,0,3,2] row_mask:0xf bank_mask:0xf
	s_nop 1
	v_add_u32_dpp v6, v6, v6 quad_perm:[2,3,0,1] row_mask:0xf bank_mask:0xf
	s_nop 1
	v_add_u32_dpp v6, v6, v6 row_ror:4 row_mask:0xf bank_mask:0xf
	s_nop 1
	v_add_u32_dpp v6, v6, v6 row_ror:8 row_mask:0xf bank_mask:0xf
	ds_swizzle_b32 v7, v6 offset:swizzle(SWAP,16)
	s_waitcnt lgkmcnt(0)
	v_add_u32_e32 v6, v6, v7
	v_cmp_gt_i32_e32 vcc, s33, v6
	s_or_b64 vcc, s[74:75], vcc
	v_cmp_eq_u32_e64 s[74:75], s33, v6
	v_cndmask_b32_e32 v66, v5, v66, vcc
	s_nop 0
	v_cndmask_b32_e64 v5, 0, 1, s[74:75]
	v_cndmask_b32_e32 v4, v5, v4, vcc
	v_and_b32_e32 v4, 1, v4
	v_cmp_eq_u32_e64 s[82:83], 1, v4
	v_cmp_eq_u32_e32 vcc, -1, v2
